# combined: aligned loop heads + first-trip peeling (no accumulator zeroing) + attention epilogue 1/l once, gate-row wait below staging, row-max v_max cleanup + single-round GEMM restart
# speedup vs baseline: 1.0025x; 1.0025x over previous
.LBB0_287:
	s_waitcnt lgkmcnt(0)
	v_mad_u64_u32 v[196:197], s[6:7], s14, v183, v[182:183]
	v_mad_u64_u32 v[194:195], s[6:7], v185, s14, v[182:183]
	v_mad_u64_u32 v[200:201], s[6:7], s14, v248, v[184:185]
	v_mad_u64_u32 v[198:199], s[6:7], v249, s14, v[184:185]
	s_sub_i32 s6, s94, 32
	s_mul_hi_u32 s7, s6, 0xaaaaaaab
	s_lshr_b32 s7, s7, 2
	s_mul_i32 s7, s7, 6
	s_sub_i32 s6, s6, s7
	s_cmp_gt_u32 s6, 1
	s_cselect_b32 s6, 1, 3
	s_cmp_gt_i32 s94, 31
	s_cselect_b32 s72, s6, 1
	s_add_u32 s6, s44, 0x80
	v_mov_b32_e32 v189, v113
	v_mov_b32_e32 v187, v113
	s_addc_u32 s7, s45, 0
	s_mov_b32 s33, 2
	v_lshl_add_u64 v[130:131], s[6:7], 0, v[188:189]
	v_lshl_add_u64 v[132:133], s[6:7], 0, v[186:187]
	s_mov_b64 s[22:23], 0x100
	s_mov_b64 s[24:25], 0
	s_mov_b64 s[6:7], 0
	s_branch .Lk1_body
	.p2align	6
